# grid barrier: waiters poll the top-level generation word directly (skip per-XCD generation hop), with early L1 invalidate
# speedup vs baseline: 1.0211x; 1.0041x over previous
; __device__ __forceinline__ unsigned xb_ld(unsigned* p) { return __hip_atomic_load(p, __ATOMIC_RELAXED, __HIP_MEMORY_SCOPE_AGENT); }
; __device__ __forceinline__ unsigned xb_add(unsigned* p, unsigned v) { return __hip_atomic_fetch_add(p, v, __ATOMIC_RELAXED, __HIP_MEMORY_SCOPE_AGENT); }
; #define XB_SPIN(cond, bar) do { unsigned _sp = 0; while (cond) { __builtin_amdgcn_s_sleep(0); \
;     if ((++_sp & 255u) == 0u) { if (xb_ld(&(bar)[XB_TMO])) break; if (_sp > XB_SPIN_CAP) { atomicAdd(&(bar)[XB_TMO], 1u); break; } } } } while (0)
; __device__ __forceinline__ void xcd_barrier(XcdBarrier& b, const int tid, const unsigned G) {
;     ...
;     const unsigned nloc = b.nloc, nx = b.nx;
;     const unsigned old = xb_add(&bar[XB_XSUB(b.x)], 1u);
;     const unsigned gen = old / nloc;
;     if (old + 1u == (gen + 1u) * nloc) {
;       __builtin_amdgcn_fence(__ATOMIC_RELEASE, "agent");
;       asm volatile("s_waitcnt vmcnt(0)" ::: "memory");
;       const unsigned og = xb_add(&bar[XB_TOP], 1u);
;       const unsigned tg = og / nx;
;       if (og + 1u == (tg + 1u) * nx) xb_add(&bar[XB_TOPGEN], 1u);
;       else XB_SPIN(xb_ld(&bar[XB_TOPGEN]) == tg, bar);
;       __builtin_amdgcn_fence(__ATOMIC_ACQUIRE, "agent");
;       xb_add(&bar[XB_XGEN(b.x)], 1u);
;       asm volatile("s_waitcnt vmcnt(0)" ::: "memory");
;     } else {
;       XB_SPIN(xb_ld(&bar[XB_XGEN(b.x)]) == gen, bar);
;       __builtin_amdgcn_fence(__ATOMIC_ACQUIRE, "agent");
;       asm volatile("s_waitcnt vmcnt(0)" ::: "memory");
.LBB0_50:
	s_or_b64 exec, exec, s[34:35]
	s_waitcnt vmcnt(0)
	v_readfirstlane_b32 s23, v1
	v_sub_u32_e32 v2, 0, v126
	s_nop 0
	v_add_u32_e32 v1, s23, v0
	v_cvt_f32_u32_e32 v0, v126
	v_rcp_iflag_f32_e32 v0, v0
	s_nop 0
	v_mul_f32_e32 v0, 0x4f7ffffe, v0
	v_cvt_u32_f32_e32 v0, v0
	v_mul_lo_u32 v2, v2, v0
	v_mul_hi_u32 v2, v0, v2
	v_add_u32_e32 v0, v0, v2
	v_mul_hi_u32 v0, v1, v0
	v_mul_lo_u32 v2, v0, v126
	v_sub_u32_e32 v2, v1, v2
	v_cmp_ge_u32_e32 vcc, v2, v126
	v_add_u32_e32 v4, 1, v0
	v_add_u32_e32 v1, 1, v1
	v_cndmask_b32_e32 v0, v0, v4, vcc
	v_sub_u32_e32 v4, v2, v126
	v_cndmask_b32_e32 v2, v2, v4, vcc
	v_cmp_ge_u32_e32 vcc, v2, v126
	v_add_u32_e32 v2, 1, v0
	s_nop 0
	v_cndmask_b32_e32 v0, v0, v2, vcc
	v_mad_u64_u32 v[4:5], s[24:25], v126, v0, v[126:127]
	v_cmp_ne_u32_e32 vcc, v1, v4
	s_and_saveexec_b64 s[24:25], vcc
	s_xor_b64 s[34:35], exec, s[24:25]
	s_cbranch_execz .LBB0_64
	v_readlane_b32 s24, v253, 15
	v_readlane_b32 s25, v253, 16
	s_nop 4
	buffer_inv sc1
	global_load_dword v1, v3, s[24:25] sc1
	s_waitcnt vmcnt(0)
	v_cmp_eq_u32_e32 vcc, v1, v0
	s_and_saveexec_b64 s[36:37], vcc
	s_cbranch_execz .LBB0_63
	s_mov_b32 s23, 1
	s_mov_b64 s[38:39], 0
	s_branch .LBB0_54

; __device__ __forceinline__ unsigned xb_ld(unsigned* p) { return __hip_atomic_load(p, __ATOMIC_RELAXED, __HIP_MEMORY_SCOPE_AGENT); }
; __device__ __forceinline__ unsigned xb_add(unsigned* p, unsigned v) { return __hip_atomic_fetch_add(p, v, __ATOMIC_RELAXED, __HIP_MEMORY_SCOPE_AGENT); }
; #define XB_SPIN(cond, bar) do { unsigned _sp = 0; while (cond) { __builtin_amdgcn_s_sleep(0); \
;     if ((++_sp & 255u) == 0u) { if (xb_ld(&(bar)[XB_TMO])) break; if (_sp > XB_SPIN_CAP) { atomicAdd(&(bar)[XB_TMO], 1u); break; } } } } while (0)
; __device__ __forceinline__ void xcd_barrier(XcdBarrier& b, const int tid, const unsigned G) {
;     ...
;       else XB_SPIN(xb_ld(&bar[XB_TOPGEN]) == tg, bar);
;       __builtin_amdgcn_fence(__ATOMIC_ACQUIRE, "agent");
;       xb_add(&bar[XB_XGEN(b.x)], 1u);
;       asm volatile("s_waitcnt vmcnt(0)" ::: "memory");
;     } else {
;       XB_SPIN(xb_ld(&bar[XB_XGEN(b.x)]) == gen, bar);
;       __builtin_amdgcn_fence(__ATOMIC_ACQUIRE, "agent");
.LBB0_56:
	v_readlane_b32 s24, v253, 15
	v_readlane_b32 s25, v253, 16
	s_add_i32 s23, s23, 1
	s_mov_b64 s[44:45], -1
	s_nop 2
	global_load_dword v1, v3, s[24:25] sc1
	s_waitcnt vmcnt(0)
	v_cmp_ne_u32_e32 vcc, v1, v0
	s_orn2_b64 s[42:43], vcc, exec
	s_branch .LBB0_53
